# sc1 write-through on the epilogue stores of the one-tile-per-CU GEMM phases (5 main, 10, 13) only
# baseline (speedup 1.0000x reference)
; __device__ __forceinline__ unsigned cvt_pk_bf16(float lo, float hi) { unsigned r; asm volatile("v_cvt_pk_bf16_f32 %0, %1, %2" : "=v"(r) : "v"(lo), "v"(hi)); return r; }
;     __device__ __forceinline__ void operator()(const f32x4 (&acc)[2][2][4][2], const Unit& u, int wr, int wc, int fr, int fq) const {
;         const int row0 = u.pm * BM + wr * 64 + fr; const int col0 = u.pn * BM + wc * 32 + 8 * fq;
;         f32x4 sv[2][2];
; #pragma unroll
;         for (int bj = 0; bj < 2; ++bj)
; #pragma unroll
;             for (int n = 0; n < 2; ++n) sv[bj][n] = (ACT == 2) ? *(const f32x4*)(cs + col0 + bj * HALF + 4 * n) : (f32x4){1.f, 1.f, 1.f, 1.f};
; #pragma unroll
;         for (int ai = 0; ai < 2; ++ai)
; #pragma unroll
;             for (int m = 0; m < 4; ++m) { bf16_t* rowp = O + (size_t)(row0 + ai * HALF + m * 16) * ldc + col0;
; #pragma unroll
;                 for (int bj = 0; bj < 2; ++bj) { f32x4 v0 = acc[ai][bj][m][0], v1 = acc[ai][bj][m][1];
;                     if (ACT == 1) { v0 = __builtin_elementwise_max(v0, (f32x4){0.f, 0.f, 0.f, 0.f}); v1 = __builtin_elementwise_max(v1, (f32x4){0.f, 0.f, 0.f, 0.f}); v0 = v0 * v0; v1 = v1 * v1; }
;                     if (ACT == 2) { v0 = v0 * sv[bj][0]; v1 = v1 * sv[bj][1]; }
;                     u32x4 w; w.x = cvt_pk_bf16(v0[0], v0[1]); w.y = cvt_pk_bf16(v0[2], v0[3]); w.z = cvt_pk_bf16(v1[0], v1[1]); w.w = cvt_pk_bf16(v1[2], v1[3]);
;                     *(u32x4*)(rowp + bj * HALF) = w; } }
.LBB0_483:
	v_lshl_add_u32 v162, s52, 8, v155
	v_lshl_or_b32 v146, s15, 8, v157
	v_ashrrev_i32_e32 v163, 31, v162
	v_ashrrev_i32_e32 v147, 31, v146
	v_lshlrev_b64 v[164:165], 11, v[162:163]
	v_lshl_add_u64 v[164:165], s[22:23], 0, v[164:165]
	v_lshlrev_b64 v[166:167], 1, v[146:147]
	v_lshl_add_u64 v[146:147], v[164:165], 0, v[166:167]
	v_cvt_pk_bf16_f32 v126, v126, v127
	v_cvt_pk_bf16_f32 v127, v128, v129
	v_cvt_pk_bf16_f32 v128, v122, v123
	v_cvt_pk_bf16_f32 v129, v124, v125
	global_store_dwordx4 v[146:147], v[126:129], off sc1
	v_cvt_pk_bf16_f32 v114, v114, v115
	v_cvt_pk_bf16_f32 v115, v116, v117
	v_cvt_pk_bf16_f32 v116, v106, v107
	v_or_b32_e32 v106, 16, v162
	v_ashrrev_i32_e32 v107, 31, v106
	v_lshlrev_b64 v[106:107], 11, v[106:107]
	v_lshl_add_u64 v[106:107], s[22:23], 0, v[106:107]
	v_cvt_pk_bf16_f32 v117, v108, v109
	global_store_dwordx4 v[146:147], v[114:117], off offset:256 sc1
	s_mov_b64 s[0:1], -1
	s_nop 0
	v_lshl_add_u64 v[114:115], v[106:107], 0, v[166:167]
	v_cvt_pk_bf16_f32 v106, v118, v119
	v_cvt_pk_bf16_f32 v107, v120, v121
	v_cvt_pk_bf16_f32 v108, v110, v111
	v_cvt_pk_bf16_f32 v109, v112, v113
	global_store_dwordx4 v[114:115], v[106:109], off sc1
	v_cvt_pk_bf16_f32 v98, v98, v99
	v_cvt_pk_bf16_f32 v99, v100, v101
	v_cvt_pk_bf16_f32 v100, v90, v91
	v_or_b32_e32 v90, 32, v162
	v_ashrrev_i32_e32 v91, 31, v90
	v_lshlrev_b64 v[90:91], 11, v[90:91]
	v_lshl_add_u64 v[90:91], s[22:23], 0, v[90:91]
	v_cvt_pk_bf16_f32 v101, v92, v93
	global_store_dwordx4 v[114:115], v[98:101], off offset:256 sc1
	s_nop 1
	v_lshl_add_u64 v[98:99], v[90:91], 0, v[166:167]
	v_cvt_pk_bf16_f32 v90, v102, v103
	v_cvt_pk_bf16_f32 v91, v104, v105
	v_cvt_pk_bf16_f32 v92, v94, v95
	v_cvt_pk_bf16_f32 v93, v96, v97
	global_store_dwordx4 v[98:99], v[90:93], off sc1
	v_cvt_pk_bf16_f32 v82, v82, v83
	v_cvt_pk_bf16_f32 v83, v84, v85
	v_cvt_pk_bf16_f32 v84, v74, v75
	v_or_b32_e32 v74, 48, v162
	v_ashrrev_i32_e32 v75, 31, v74
	v_lshlrev_b64 v[74:75], 11, v[74:75]
	v_lshl_add_u64 v[74:75], s[22:23], 0, v[74:75]
	v_cvt_pk_bf16_f32 v85, v76, v77
	global_store_dwordx4 v[98:99], v[82:85], off offset:256 sc1
	s_nop 1
	v_lshl_add_u64 v[82:83], v[74:75], 0, v[166:167]
	v_cvt_pk_bf16_f32 v74, v86, v87
	v_cvt_pk_bf16_f32 v75, v88, v89
	v_cvt_pk_bf16_f32 v76, v78, v79
	v_cvt_pk_bf16_f32 v77, v80, v81
	global_store_dwordx4 v[82:83], v[74:77], off sc1
	v_cvt_pk_bf16_f32 v70, v70, v71
	v_cvt_pk_bf16_f32 v71, v72, v73
	v_cvt_pk_bf16_f32 v72, v66, v67
	v_cvt_pk_bf16_f32 v73, v68, v69
	global_store_dwordx4 v[82:83], v[70:73], off offset:256 sc1
	v_cvt_pk_bf16_f32 v62, v62, v63
	v_cvt_pk_bf16_f32 v63, v64, v65
	v_cvt_pk_bf16_f32 v64, v58, v59
	v_add_co_u32_e32 v58, vcc, s80, v146
	v_lshl_add_u64 v[66:67], v[146:147], 0, s[30:31]
	s_nop 0
	v_addc_co_u32_e32 v59, vcc, 0, v147, vcc
	v_cvt_pk_bf16_f32 v65, v60, v61
	global_store_dwordx4 v[58:59], v[62:65], off sc1
	v_cvt_pk_bf16_f32 v50, v50, v51
	v_cvt_pk_bf16_f32 v51, v52, v53
	v_cvt_pk_bf16_f32 v52, v42, v43
	v_cvt_pk_bf16_f32 v53, v44, v45
	global_store_dwordx4 v[66:67], v[50:53], off offset:256 sc1
	v_cvt_pk_bf16_f32 v42, v54, v55
	v_cvt_pk_bf16_f32 v43, v56, v57
	v_cvt_pk_bf16_f32 v44, v46, v47
	v_add_co_u32_e32 v46, vcc, s81, v146
	s_nop 0
	v_lshl_add_u64 v[50:51], v[146:147], 0, s[36:37]
	v_addc_co_u32_e32 v47, vcc, 0, v147, vcc
	v_cvt_pk_bf16_f32 v45, v48, v49
	global_store_dwordx4 v[46:47], v[42:45], off sc1
	v_cvt_pk_bf16_f32 v34, v34, v35
	v_cvt_pk_bf16_f32 v35, v36, v37
	v_cvt_pk_bf16_f32 v36, v26, v27
	v_cvt_pk_bf16_f32 v37, v28, v29
	global_store_dwordx4 v[50:51], v[34:37], off offset:256 sc1
	v_cvt_pk_bf16_f32 v26, v38, v39
	v_cvt_pk_bf16_f32 v27, v40, v41
	v_cvt_pk_bf16_f32 v28, v30, v31
	v_add_co_u32_e32 v30, vcc, s82, v146
	s_nop 0
	v_lshl_add_u64 v[34:35], v[146:147], 0, s[38:39]
	v_addc_co_u32_e32 v31, vcc, 0, v147, vcc
	v_cvt_pk_bf16_f32 v29, v32, v33
	global_store_dwordx4 v[30:31], v[26:29], off sc1
	v_cvt_pk_bf16_f32 v18, v18, v19
	v_cvt_pk_bf16_f32 v19, v20, v21
	v_cvt_pk_bf16_f32 v20, v10, v11
	v_cvt_pk_bf16_f32 v21, v12, v13
	global_store_dwordx4 v[34:35], v[18:21], off offset:256 sc1
	v_cvt_pk_bf16_f32 v10, v22, v23
	v_cvt_pk_bf16_f32 v11, v24, v25
	v_cvt_pk_bf16_f32 v12, v14, v15
	v_add_co_u32_e32 v14, vcc, s83, v146
	s_nop 0
	v_lshl_add_u64 v[18:19], v[146:147], 0, s[40:41]
	v_addc_co_u32_e32 v15, vcc, 0, v147, vcc
	s_and_b64 vcc, exec, s[2:3]
	v_cvt_pk_bf16_f32 v13, v16, v17
	global_store_dwordx4 v[14:15], v[10:13], off sc1
	v_cvt_pk_bf16_f32 v6, v6, v7
	v_cvt_pk_bf16_f32 v7, v8, v9
	v_cvt_pk_bf16_f32 v8, v2, v3
	v_cvt_pk_bf16_f32 v9, v4, v5
	global_store_dwordx4 v[18:19], v[6:9], off offset:256 sc1
	s_cbranch_vccnz .LBB0_470
	s_andn2_b64 vcc, exec, s[6:7]
	s_cbranch_vccnz .LBB0_469
	s_barrier
	s_branch .LBB0_469

; __device__ __forceinline__ unsigned cvt_pk_bf16(float lo, float hi) { unsigned r; asm volatile("v_cvt_pk_bf16_f32 %0, %1, %2" : "=v"(r) : "v"(lo), "v"(hi)); return r; }
;     __device__ __forceinline__ void operator()(const f32x4 (&acc)[2][2][4][2], const Unit& u, int wr, int wc, int fr, int fq) const {
;         const int row0 = u.pm * BM + wr * 64 + fr; const int col0 = u.pn * BM + wc * 32 + 8 * fq;
;         f32x4 sv[2][2];
; #pragma unroll
;         for (int bj = 0; bj < 2; ++bj)
; #pragma unroll
;             for (int n = 0; n < 2; ++n) sv[bj][n] = (ACT == 2) ? *(const f32x4*)(cs + col0 + bj * HALF + 4 * n) : (f32x4){1.f, 1.f, 1.f, 1.f};
; #pragma unroll
;         for (int ai = 0; ai < 2; ++ai)
; #pragma unroll
;             for (int m = 0; m < 4; ++m) { bf16_t* rowp = O + (size_t)(row0 + ai * HALF + m * 16) * ldc + col0;
; #pragma unroll
;                 for (int bj = 0; bj < 2; ++bj) { f32x4 v0 = acc[ai][bj][m][0], v1 = acc[ai][bj][m][1];
;                     if (ACT == 1) { v0 = __builtin_elementwise_max(v0, (f32x4){0.f, 0.f, 0.f, 0.f}); v1 = __builtin_elementwise_max(v1, (f32x4){0.f, 0.f, 0.f, 0.f}); v0 = v0 * v0; v1 = v1 * v1; }
;                     if (ACT == 2) { v0 = v0 * sv[bj][0]; v1 = v1 * sv[bj][1]; }
;                     u32x4 w; w.x = cvt_pk_bf16(v0[0], v0[1]); w.y = cvt_pk_bf16(v0[2], v0[3]); w.z = cvt_pk_bf16(v1[0], v1[1]); w.w = cvt_pk_bf16(v1[2], v1[3]);
;                     *(u32x4*)(rowp + bj * HALF) = w; } }
.LBB0_902:
	v_lshl_add_u32 v154, s42, 8, v1
	v_lshl_or_b32 v146, s79, 8, v149
	v_ashrrev_i32_e32 v155, 31, v154
	v_ashrrev_i32_e32 v147, 31, v146
	v_lshlrev_b64 v[156:157], 11, v[154:155]
	v_lshl_add_u64 v[156:157], s[22:23], 0, v[156:157]
	v_lshlrev_b64 v[158:159], 1, v[146:147]
	v_lshl_add_u64 v[146:147], v[156:157], 0, v[158:159]
	v_cvt_pk_bf16_f32 v126, v126, v127
	v_cvt_pk_bf16_f32 v127, v128, v129
	v_cvt_pk_bf16_f32 v128, v122, v123
	v_cvt_pk_bf16_f32 v129, v124, v125
	global_store_dwordx4 v[146:147], v[126:129], off sc1
	v_cvt_pk_bf16_f32 v114, v114, v115
	v_cvt_pk_bf16_f32 v115, v116, v117
	v_cvt_pk_bf16_f32 v116, v106, v107
	v_or_b32_e32 v106, 16, v154
	v_ashrrev_i32_e32 v107, 31, v106
	v_lshlrev_b64 v[106:107], 11, v[106:107]
	v_lshl_add_u64 v[106:107], s[22:23], 0, v[106:107]
	v_cvt_pk_bf16_f32 v117, v108, v109
	global_store_dwordx4 v[146:147], v[114:117], off offset:256 sc1
	s_mov_b64 s[0:1], -1
	s_nop 0
	v_lshl_add_u64 v[114:115], v[106:107], 0, v[158:159]
	v_cvt_pk_bf16_f32 v106, v118, v119
	v_cvt_pk_bf16_f32 v107, v120, v121
	v_cvt_pk_bf16_f32 v108, v110, v111
	v_cvt_pk_bf16_f32 v109, v112, v113
	global_store_dwordx4 v[114:115], v[106:109], off sc1
	v_cvt_pk_bf16_f32 v98, v98, v99
	v_cvt_pk_bf16_f32 v99, v100, v101
	v_cvt_pk_bf16_f32 v100, v90, v91
	v_or_b32_e32 v90, 32, v154
	v_ashrrev_i32_e32 v91, 31, v90
	v_lshlrev_b64 v[90:91], 11, v[90:91]
	v_lshl_add_u64 v[90:91], s[22:23], 0, v[90:91]
	v_cvt_pk_bf16_f32 v101, v92, v93
	global_store_dwordx4 v[114:115], v[98:101], off offset:256 sc1
	s_nop 1
	v_lshl_add_u64 v[98:99], v[90:91], 0, v[158:159]
	v_cvt_pk_bf16_f32 v90, v102, v103
	v_cvt_pk_bf16_f32 v91, v104, v105
	v_cvt_pk_bf16_f32 v92, v94, v95
	v_cvt_pk_bf16_f32 v93, v96, v97
	global_store_dwordx4 v[98:99], v[90:93], off sc1
	v_cvt_pk_bf16_f32 v82, v82, v83
	v_cvt_pk_bf16_f32 v83, v84, v85
	v_cvt_pk_bf16_f32 v84, v74, v75
	v_or_b32_e32 v74, 48, v154
	v_ashrrev_i32_e32 v75, 31, v74
	v_lshlrev_b64 v[74:75], 11, v[74:75]
	v_lshl_add_u64 v[74:75], s[22:23], 0, v[74:75]
	v_cvt_pk_bf16_f32 v85, v76, v77
	global_store_dwordx4 v[98:99], v[82:85], off offset:256 sc1
	s_nop 1
	v_lshl_add_u64 v[82:83], v[74:75], 0, v[158:159]
	v_cvt_pk_bf16_f32 v74, v86, v87
	v_cvt_pk_bf16_f32 v75, v88, v89
	v_cvt_pk_bf16_f32 v76, v78, v79
	v_cvt_pk_bf16_f32 v77, v80, v81
	global_store_dwordx4 v[82:83], v[74:77], off sc1
	v_cvt_pk_bf16_f32 v70, v70, v71
	v_cvt_pk_bf16_f32 v71, v72, v73
	v_cvt_pk_bf16_f32 v72, v66, v67
	v_cvt_pk_bf16_f32 v73, v68, v69
	global_store_dwordx4 v[82:83], v[70:73], off offset:256 sc1
	v_cvt_pk_bf16_f32 v62, v62, v63
	v_cvt_pk_bf16_f32 v63, v64, v65
	v_cvt_pk_bf16_f32 v64, v58, v59
	v_add_co_u32_e32 v58, vcc, s74, v146
	v_lshl_add_u64 v[66:67], v[146:147], 0, s[6:7]
	s_nop 0
	v_addc_co_u32_e32 v59, vcc, 0, v147, vcc
	v_cvt_pk_bf16_f32 v65, v60, v61
	global_store_dwordx4 v[58:59], v[62:65], off sc1
	v_cvt_pk_bf16_f32 v50, v50, v51
	v_cvt_pk_bf16_f32 v51, v52, v53
	v_cvt_pk_bf16_f32 v52, v42, v43
	v_cvt_pk_bf16_f32 v53, v44, v45
	global_store_dwordx4 v[66:67], v[50:53], off offset:256 sc1
	v_cvt_pk_bf16_f32 v42, v54, v55
	v_cvt_pk_bf16_f32 v43, v56, v57
	v_cvt_pk_bf16_f32 v44, v46, v47
	v_add_co_u32_e32 v46, vcc, s75, v146
	s_nop 0
	v_lshl_add_u64 v[50:51], v[146:147], 0, s[26:27]
	v_addc_co_u32_e32 v47, vcc, 0, v147, vcc
	v_cvt_pk_bf16_f32 v45, v48, v49
	global_store_dwordx4 v[46:47], v[42:45], off sc1
	v_cvt_pk_bf16_f32 v34, v34, v35
	v_cvt_pk_bf16_f32 v35, v36, v37
	v_cvt_pk_bf16_f32 v36, v26, v27
	v_cvt_pk_bf16_f32 v37, v28, v29
	global_store_dwordx4 v[50:51], v[34:37], off offset:256 sc1
	v_cvt_pk_bf16_f32 v26, v38, v39
	v_cvt_pk_bf16_f32 v27, v40, v41
	v_cvt_pk_bf16_f32 v28, v30, v31
	v_add_co_u32_e32 v30, vcc, s76, v146
	s_nop 0
	v_lshl_add_u64 v[34:35], v[146:147], 0, s[28:29]
	v_addc_co_u32_e32 v31, vcc, 0, v147, vcc
	v_cvt_pk_bf16_f32 v29, v32, v33
	global_store_dwordx4 v[30:31], v[26:29], off sc1
	v_cvt_pk_bf16_f32 v18, v18, v19
	v_cvt_pk_bf16_f32 v19, v20, v21
	v_cvt_pk_bf16_f32 v20, v10, v11
	v_cvt_pk_bf16_f32 v21, v12, v13
	global_store_dwordx4 v[34:35], v[18:21], off offset:256 sc1
	v_cvt_pk_bf16_f32 v10, v22, v23
	v_cvt_pk_bf16_f32 v11, v24, v25
	v_cvt_pk_bf16_f32 v12, v14, v15
	v_add_co_u32_e32 v14, vcc, s77, v146
	s_nop 0
	v_lshl_add_u64 v[18:19], v[146:147], 0, s[30:31]
	v_addc_co_u32_e32 v15, vcc, 0, v147, vcc
	s_and_b64 vcc, exec, s[2:3]
	v_cvt_pk_bf16_f32 v13, v16, v17
	global_store_dwordx4 v[14:15], v[10:13], off sc1
	v_cvt_pk_bf16_f32 v6, v6, v7
	v_cvt_pk_bf16_f32 v7, v8, v9
	v_cvt_pk_bf16_f32 v8, v2, v3
	v_cvt_pk_bf16_f32 v9, v4, v5
	global_store_dwordx4 v[18:19], v[6:9], off offset:256 sc1
	s_cbranch_vccnz .LBB0_889
	s_andn2_b64 vcc, exec, s[8:9]
	s_cbranch_vccnz .LBB0_888
	s_barrier
	s_branch .LBB0_888

; __device__ __forceinline__ unsigned cvt_pk_bf16(float lo, float hi) { unsigned r; asm volatile("v_cvt_pk_bf16_f32 %0, %1, %2" : "=v"(r) : "v"(lo), "v"(hi)); return r; }
;     __device__ __forceinline__ void operator()(const f32x4 (&acc)[2][2][4][2], const Unit& u, int wr, int wc, int fr, int fq) const {
;         const int row0 = u.pm * BM + wr * 64 + fr; const int col0 = u.pn * BM + wc * 32 + 8 * fq;
;         f32x4 sv[2][2];
; #pragma unroll
;         for (int bj = 0; bj < 2; ++bj)
; #pragma unroll
;             for (int n = 0; n < 2; ++n) sv[bj][n] = (ACT == 2) ? *(const f32x4*)(cs + col0 + bj * HALF + 4 * n) : (f32x4){1.f, 1.f, 1.f, 1.f};
; #pragma unroll
;         for (int ai = 0; ai < 2; ++ai)
; #pragma unroll
;             for (int m = 0; m < 4; ++m) { bf16_t* rowp = O + (size_t)(row0 + ai * HALF + m * 16) * ldc + col0;
; #pragma unroll
;                 for (int bj = 0; bj < 2; ++bj) { f32x4 v0 = acc[ai][bj][m][0], v1 = acc[ai][bj][m][1];
;                     if (ACT == 1) { v0 = __builtin_elementwise_max(v0, (f32x4){0.f, 0.f, 0.f, 0.f}); v1 = __builtin_elementwise_max(v1, (f32x4){0.f, 0.f, 0.f, 0.f}); v0 = v0 * v0; v1 = v1 * v1; }
;                     if (ACT == 2) { v0 = v0 * sv[bj][0]; v1 = v1 * sv[bj][1]; }
;                     u32x4 w; w.x = cvt_pk_bf16(v0[0], v0[1]); w.y = cvt_pk_bf16(v0[2], v0[3]); w.z = cvt_pk_bf16(v1[0], v1[1]); w.w = cvt_pk_bf16(v1[2], v1[3]);
;                     *(u32x4*)(rowp + bj * HALF) = w; } }
.LBB0_1124:
	v_lshl_add_u32 v152, s40, 8, v146
	v_lshl_or_b32 v144, s73, 8, v148
	v_ashrrev_i32_e32 v153, 31, v152
	v_ashrrev_i32_e32 v145, 31, v144
	v_lshlrev_b64 v[154:155], 11, v[152:153]
	v_lshl_add_u64 v[154:155], s[22:23], 0, v[154:155]
	v_lshlrev_b64 v[156:157], 1, v[144:145]
	v_lshl_add_u64 v[144:145], v[154:155], 0, v[156:157]
	v_cvt_pk_bf16_f32 v124, v124, v125
	v_cvt_pk_bf16_f32 v125, v126, v127
	v_cvt_pk_bf16_f32 v126, v120, v121
	v_cvt_pk_bf16_f32 v127, v122, v123
	global_store_dwordx4 v[144:145], v[124:127], off sc1
	v_cvt_pk_bf16_f32 v112, v112, v113
	v_cvt_pk_bf16_f32 v113, v114, v115
	v_cvt_pk_bf16_f32 v114, v104, v105
	v_or_b32_e32 v104, 16, v152
	v_ashrrev_i32_e32 v105, 31, v104
	v_lshlrev_b64 v[104:105], 11, v[104:105]
	v_lshl_add_u64 v[104:105], s[22:23], 0, v[104:105]
	v_cvt_pk_bf16_f32 v115, v106, v107
	global_store_dwordx4 v[144:145], v[112:115], off offset:256 sc1
	s_mov_b64 s[0:1], -1
	s_nop 0
	v_lshl_add_u64 v[112:113], v[104:105], 0, v[156:157]
	v_cvt_pk_bf16_f32 v104, v116, v117
	v_cvt_pk_bf16_f32 v105, v118, v119
	v_cvt_pk_bf16_f32 v106, v108, v109
	v_cvt_pk_bf16_f32 v107, v110, v111
	global_store_dwordx4 v[112:113], v[104:107], off sc1
	v_cvt_pk_bf16_f32 v96, v96, v97
	v_cvt_pk_bf16_f32 v97, v98, v99
	v_cvt_pk_bf16_f32 v98, v88, v89
	v_or_b32_e32 v88, 32, v152
	v_ashrrev_i32_e32 v89, 31, v88
	v_lshlrev_b64 v[88:89], 11, v[88:89]
	v_lshl_add_u64 v[88:89], s[22:23], 0, v[88:89]
	v_cvt_pk_bf16_f32 v99, v90, v91
	global_store_dwordx4 v[112:113], v[96:99], off offset:256 sc1
	s_nop 1
	v_lshl_add_u64 v[96:97], v[88:89], 0, v[156:157]
	v_cvt_pk_bf16_f32 v88, v100, v101
	v_cvt_pk_bf16_f32 v89, v102, v103
	v_cvt_pk_bf16_f32 v90, v92, v93
	v_cvt_pk_bf16_f32 v91, v94, v95
	global_store_dwordx4 v[96:97], v[88:91], off sc1
	v_cvt_pk_bf16_f32 v80, v80, v81
	v_cvt_pk_bf16_f32 v81, v82, v83
	v_cvt_pk_bf16_f32 v82, v72, v73
	v_or_b32_e32 v72, 48, v152
	v_ashrrev_i32_e32 v73, 31, v72
	v_lshlrev_b64 v[72:73], 11, v[72:73]
	v_lshl_add_u64 v[72:73], s[22:23], 0, v[72:73]
	v_cvt_pk_bf16_f32 v83, v74, v75
	global_store_dwordx4 v[96:97], v[80:83], off offset:256 sc1
	s_nop 1
	v_lshl_add_u64 v[80:81], v[72:73], 0, v[156:157]
	v_cvt_pk_bf16_f32 v72, v84, v85
	v_cvt_pk_bf16_f32 v73, v86, v87
	v_cvt_pk_bf16_f32 v74, v76, v77
	v_cvt_pk_bf16_f32 v75, v78, v79
	global_store_dwordx4 v[80:81], v[72:75], off sc1
	v_cvt_pk_bf16_f32 v68, v68, v69
	v_cvt_pk_bf16_f32 v69, v70, v71
	v_cvt_pk_bf16_f32 v70, v64, v65
	v_cvt_pk_bf16_f32 v71, v66, v67
	global_store_dwordx4 v[80:81], v[68:71], off offset:256 sc1
	v_cvt_pk_bf16_f32 v60, v60, v61
	v_cvt_pk_bf16_f32 v61, v62, v63
	v_cvt_pk_bf16_f32 v62, v56, v57
	v_add_co_u32_e32 v56, vcc, s68, v144
	v_lshl_add_u64 v[64:65], v[144:145], 0, s[16:17]
	s_nop 0
	v_addc_co_u32_e32 v57, vcc, 0, v145, vcc
	v_cvt_pk_bf16_f32 v63, v58, v59
	global_store_dwordx4 v[56:57], v[60:63], off sc1
	v_cvt_pk_bf16_f32 v48, v48, v49
	v_cvt_pk_bf16_f32 v49, v50, v51
	v_cvt_pk_bf16_f32 v50, v40, v41
	v_cvt_pk_bf16_f32 v51, v42, v43
	global_store_dwordx4 v[64:65], v[48:51], off offset:256 sc1
	v_cvt_pk_bf16_f32 v40, v52, v53
	v_cvt_pk_bf16_f32 v41, v54, v55
	v_cvt_pk_bf16_f32 v42, v44, v45
	v_add_co_u32_e32 v44, vcc, s69, v144
	s_nop 0
	v_lshl_add_u64 v[48:49], v[144:145], 0, s[24:25]
	v_addc_co_u32_e32 v45, vcc, 0, v145, vcc
	v_cvt_pk_bf16_f32 v43, v46, v47
	global_store_dwordx4 v[44:45], v[40:43], off sc1
	v_cvt_pk_bf16_f32 v32, v32, v33
	v_cvt_pk_bf16_f32 v33, v34, v35
	v_cvt_pk_bf16_f32 v34, v24, v25
	v_cvt_pk_bf16_f32 v35, v26, v27
	global_store_dwordx4 v[48:49], v[32:35], off offset:256 sc1
	v_cvt_pk_bf16_f32 v24, v36, v37
	v_cvt_pk_bf16_f32 v25, v38, v39
	v_cvt_pk_bf16_f32 v26, v28, v29
	v_add_co_u32_e32 v28, vcc, s70, v144
	s_nop 0
	v_lshl_add_u64 v[32:33], v[144:145], 0, s[26:27]
	v_addc_co_u32_e32 v29, vcc, 0, v145, vcc
	v_cvt_pk_bf16_f32 v27, v30, v31
	global_store_dwordx4 v[28:29], v[24:27], off sc1
	v_cvt_pk_bf16_f32 v16, v16, v17
	v_cvt_pk_bf16_f32 v17, v18, v19
	v_cvt_pk_bf16_f32 v18, v8, v9
	v_cvt_pk_bf16_f32 v19, v10, v11
	global_store_dwordx4 v[32:33], v[16:19], off offset:256 sc1
	v_cvt_pk_bf16_f32 v8, v20, v21
	v_cvt_pk_bf16_f32 v9, v22, v23
	v_cvt_pk_bf16_f32 v10, v12, v13
	v_add_co_u32_e32 v12, vcc, s71, v144
	s_nop 0
	v_lshl_add_u64 v[16:17], v[144:145], 0, s[28:29]
	v_addc_co_u32_e32 v13, vcc, 0, v145, vcc
	s_and_b64 vcc, exec, s[2:3]
	v_cvt_pk_bf16_f32 v11, v14, v15
	global_store_dwordx4 v[12:13], v[8:11], off sc1
	v_cvt_pk_bf16_f32 v4, v4, v5
	v_cvt_pk_bf16_f32 v5, v6, v7
	v_cvt_pk_bf16_f32 v6, v0, v1
	v_cvt_pk_bf16_f32 v7, v2, v3
	global_store_dwordx4 v[16:17], v[4:7], off offset:256 sc1
	s_cbranch_vccnz .LBB0_1111
	s_andn2_b64 vcc, exec, s[6:7]
	s_cbranch_vccnz .LBB0_1110
	s_barrier
	s_branch .LBB0_1110
